# plus: removed the acquire buffer_inv in the row-statistics exchange (its slot loads are sc1, L1-bypassing)
# speedup vs baseline: 1.0078x; 1.0078x over previous
.LBB0_429:
	s_andn2_b64 vcc, exec, s[90:91]
	s_cbranch_vccz .LBB0_435
	s_waitcnt lgkmcnt(0)
	s_and_saveexec_b64 s[18:19], s[14:15]
	s_xor_b64 s[18:19], exec, s[18:19]
	s_cbranch_execz .LBB0_432
.LBB0_432:
	s_or_saveexec_b64 s[88:89], s[18:19]
	s_mov_b64 s[18:19], 0
	s_xor_b64 exec, exec, s[88:89]
	s_cbranch_execz .LBB0_434
	s_and_b32 s18, s56, 0xff
	s_or_b32 s18, s18, 0x700
	v_mov_b32_e32 v210, s18
	s_load_dwordx2 s[18:19], s[0:1], 0x80
	v_mov_b32_e32 v211, v223
	s_waitcnt lgkmcnt(0)
	global_atomic_cmpswap v223, v[210:211], s[18:19] offset:4
	global_store_dword v223, v240, s[18:19] sc1
	s_mov_b64 s[18:19], exec

.LBB0_436:
	s_waitcnt vmcnt(0)
	s_and_b64 exec, exec, s[12:13]
	v_cndmask_b32_e64 v210, 0, 1, s[88:89]
	ds_write_b32 v223, v210 offset:10240

.LBB0_598:
	s_andn2_b64 vcc, exec, s[20:21]
	s_cbranch_vccz .LBB0_604
	s_waitcnt lgkmcnt(0)
	s_and_saveexec_b64 s[8:9], s[14:15]
	s_xor_b64 s[8:9], exec, s[8:9]
	s_cbranch_execz .LBB0_601
.LBB0_601:
	s_or_saveexec_b64 s[14:15], s[8:9]
	s_mov_b64 s[8:9], 0
	s_xor_b64 exec, exec, s[14:15]
	s_cbranch_execz .LBB0_603
	s_and_b32 s8, s56, 0x7f
	s_or_b32 s8, s8, 0x780
	v_mov_b32_e32 v222, s8
	s_load_dwordx2 s[8:9], s[0:1], 0x80
	s_waitcnt lgkmcnt(0)
	global_atomic_cmpswap v223, v[222:223], s[8:9] offset:4
	global_store_dword v223, v240, s[8:9] sc1
	s_mov_b64 s[8:9], exec

.LBB0_605:
	s_waitcnt vmcnt(0)
	s_and_b64 exec, exec, s[12:13]
	v_cndmask_b32_e64 v164, 0, 1, s[14:15]
	ds_write_b32 v223, v164 offset:10240

.LBB0_1224:
	s_andn2_b64 vcc, exec, s[78:79]
	s_cbranch_vccz .LBB0_1230
	s_waitcnt lgkmcnt(0)
	s_and_saveexec_b64 s[16:17], s[12:13]
	s_xor_b64 s[16:17], exec, s[16:17]
	s_cbranch_execz .LBB0_1227
.LBB0_1227:
	s_or_saveexec_b64 s[76:77], s[16:17]
	s_mov_b64 s[16:17], 0
	s_xor_b64 exec, exec, s[76:77]
	s_cbranch_execz .LBB0_1229
	s_and_b32 s16, s82, 0xff
	s_or_b32 s16, s16, 0x700
	v_mov_b32_e32 v210, s16
	s_load_dwordx2 s[16:17], s[0:1], 0x80
	v_mov_b32_e32 v211, v223
	s_waitcnt lgkmcnt(0)
	global_atomic_cmpswap v223, v[210:211], s[16:17] offset:4
	global_store_dword v223, v240, s[16:17] sc1
	s_mov_b64 s[16:17], exec

.LBB0_1231:
	s_waitcnt vmcnt(0)
	s_and_b64 exec, exec, s[10:11]
	v_cndmask_b32_e64 v210, 0, 1, s[76:77]
	ds_write_b32 v223, v210 offset:10240

.LBB0_1393:
	s_andn2_b64 vcc, exec, s[18:19]
	s_cbranch_vccz .LBB0_1399
	s_waitcnt lgkmcnt(0)
	s_and_saveexec_b64 s[6:7], s[12:13]
	s_xor_b64 s[6:7], exec, s[6:7]
	s_cbranch_execz .LBB0_1396
.LBB0_1396:
	s_or_saveexec_b64 s[12:13], s[6:7]
	s_mov_b64 s[6:7], 0
	s_xor_b64 exec, exec, s[12:13]
	s_cbranch_execz .LBB0_1398
	s_and_b32 s6, s82, 0x7f
	s_or_b32 s6, s6, 0x780
	v_mov_b32_e32 v222, s6
	s_load_dwordx2 s[6:7], s[0:1], 0x80
	s_waitcnt lgkmcnt(0)
	global_atomic_cmpswap v223, v[222:223], s[6:7] offset:4
	global_store_dword v223, v240, s[6:7] sc1
	s_mov_b64 s[6:7], exec

.LBB0_1400:
	s_waitcnt vmcnt(0)
	s_and_b64 exec, exec, s[10:11]
	v_cndmask_b32_e64 v164, 0, 1, s[12:13]
	ds_write_b32 v223, v164 offset:10240
